# ln_router L0: token-invariant LN gamma/beta loads hoisted out of the token loop
# speedup vs baseline: 1.0045x; 1.0045x over previous
.LBB0_833:
	s_or_b64 exec, exec, s[0:1]
	s_waitcnt vmcnt(3)
	v_ashrrev_i32_e32 v0, 6, v2
	s_lshl_b32 s96, s55, 2
	v_add_u32_e32 v48, s96, v0
	s_movk_i32 s10, 0x2000
	v_cmp_gt_i32_e32 vcc, s10, v48
	s_waitcnt lgkmcnt(0)
	s_barrier
	s_and_saveexec_b64 s[36:37], vcc
	s_cbranch_execz .LBB0_842
	v_readlane_b32 s12, v253, 50
	v_readlane_b32 s13, v253, 51
	v_readlane_b32 s14, v253, 52
	v_readlane_b32 s15, v253, 53
	v_readlane_b32 s24, v253, 62
	v_readlane_b32 s25, v253, 63
	v_ashrrev_i32_e32 v49, 31, v48
	v_readlane_b32 s26, v255, 0
	v_readlane_b32 s27, v255, 1
	s_mov_b64 s[12:13], s[24:25]
	v_and_b32_e32 v50, 63, v2
	v_lshlrev_b64 v[0:1], 12, v[48:49]
	s_mov_b64 s[14:15], s[26:27]
	v_mov_b32_e32 v51, 0
	v_lshl_add_u64 v[4:5], s[14:15], 0, v[0:1]
	v_lshlrev_b32_e32 v52, 4, v50
	v_mov_b32_e32 v53, v51
	v_lshl_add_u64 v[4:5], v[4:5], 0, v[52:53]
	v_and_b32_e32 v1, 32, v2
	v_cmp_eq_u32_e64 s[34:35], 0, v1
	v_and_b32_e32 v1, 16, v2
	v_cmp_eq_u32_e64 s[4:5], 0, v1
	v_and_b32_e32 v1, 8, v2
	v_cmp_eq_u32_e64 s[6:7], 0, v1
	v_and_b32_e32 v1, 4, v2
	v_cmp_eq_u32_e64 s[8:9], 0, v1
	v_mbcnt_lo_u32_b32 v1, -1, 0
	v_mbcnt_hi_u32_b32 v1, -1, v1
	v_and_b32_e32 v4, 64, v1
	v_xor_b32_e32 v3, 8, v1
	v_add_u32_e32 v4, 64, v4
	v_cmp_lt_i32_e32 vcc, v3, v4
	v_readlane_b32 s16, v253, 54
	v_readlane_b32 s17, v253, 55
	v_cndmask_b32_e32 v3, v1, v3, vcc
	v_lshlrev_b32_e32 v77, 2, v3
	v_xor_b32_e32 v3, 4, v1
	v_cmp_lt_i32_e32 vcc, v3, v4
	v_readlane_b32 s18, v253, 56
	v_readlane_b32 s19, v253, 57
	v_cndmask_b32_e32 v3, v1, v3, vcc
	v_lshlrev_b32_e32 v84, 2, v3
	v_xor_b32_e32 v3, 2, v1
	v_cmp_lt_i32_e32 vcc, v3, v4
	v_readlane_b32 s20, v253, 58
	v_readlane_b32 s21, v253, 59
	v_cndmask_b32_e32 v3, v1, v3, vcc
	v_lshlrev_b32_e32 v85, 2, v3
	v_xor_b32_e32 v3, 1, v1
	v_readlane_b32 s22, v253, 60
	v_readlane_b32 s23, v253, 61
	v_cmp_lt_i32_e32 vcc, v3, v4
	v_lshlrev_b32_e32 v0, 2, v50
	v_readlane_b32 s16, v254, 18
	v_cndmask_b32_e32 v1, v1, v3, vcc
	v_readlane_b32 s76, v253, 26
	v_lshlrev_b32_e32 v86, 2, v1
	v_and_b32_e32 v1, 3, v2
	v_cmp_eq_u32_e64 s[12:13], 1, v50
	v_readlane_b32 s22, v254, 24
	v_readlane_b32 s23, v254, 25
	v_readlane_b32 s24, v254, 26
	v_readlane_b32 s25, v254, 27
	v_or_b32_e32 v2, 0x100, v0
	v_or_b32_e32 v4, 0x200, v0
	v_or_b32_e32 v6, 0x300, v0
	v_lshl_add_u64 v[60:61], s[66:67], 0, v[50:51]
	v_lshlrev_b32_e32 v50, 3, v50
	v_readlane_b32 s77, v253, 27
	s_lshl_b32 s11, s92, 2
	v_cmp_eq_u32_e64 s[0:1], 0, v1
	v_lshl_add_u64 v[54:55], s[22:23], 0, v[52:53]
	v_lshl_add_u64 v[56:57], s[24:25], 0, v[52:53]
	v_lshl_add_u64 v[58:59], s[14:15], 0, v[52:53]
	v_lshl_add_u64 v[62:63], s[64:65], 0, v[50:51]
	s_mov_b64 s[22:23], 0
	v_mov_b64_e32 v[64:65], s[76:77]
	v_lshlrev_b32_e32 v50, 2, v0
	v_lshlrev_b32_e32 v66, 2, v2
	v_mov_b32_e32 v67, v51
	v_lshlrev_b32_e32 v68, 2, v4
	v_mov_b32_e32 v69, v51
	v_lshlrev_b32_e32 v70, 2, v6
	v_mov_b32_e32 v71, v51
	v_mov_b32_e32 v53, 0x7f800000
	v_readlane_b32 s17, v254, 19
	v_readlane_b32 s18, v254, 20
	v_readlane_b32 s19, v254, 21
	v_readlane_b32 s20, v254, 22
	v_readlane_b32 s21, v254, 23
	v_readlane_b32 s26, v254, 28
	v_readlane_b32 s27, v254, 29
	v_readlane_b32 s28, v254, 30
	v_readlane_b32 s29, v254, 31
	s_waitcnt vmcnt(3)
	v_mov_b64_e32 v[0:1], v[28:29]
	v_mov_b64_e32 v[2:3], v[30:31]
	s_waitcnt vmcnt(2)
	v_mov_b64_e32 v[4:5], v[24:25]
	v_mov_b64_e32 v[6:7], v[26:27]
	s_waitcnt vmcnt(1)
	v_mov_b64_e32 v[8:9], v[20:21]
	v_mov_b64_e32 v[10:11], v[22:23]
	s_waitcnt vmcnt(0)
	v_mov_b64_e32 v[12:13], v[16:17]
	v_mov_b64_e32 v[14:15], v[18:19]
	v_readlane_b32 s30, v254, 32
	v_readlane_b32 s31, v254, 33
	v_readlane_b32 s78, v253, 28
	v_readlane_b32 s79, v253, 29
	v_readlane_b32 s80, v253, 30
	v_readlane_b32 s81, v253, 31
	v_readlane_b32 s82, v253, 32
	v_readlane_b32 s83, v253, 33
	v_readlane_b32 s84, v253, 34
	v_readlane_b32 s85, v253, 35
	v_readlane_b32 s86, v253, 36
	v_readlane_b32 s87, v253, 37
	v_readlane_b32 s88, v253, 38
	v_readlane_b32 s89, v253, 39
	v_readlane_b32 s90, v253, 40
	v_readlane_b32 s91, v253, 41
	global_load_dwordx4 v[100:103], v[54:55], off
	global_load_dwordx4 v[104:107], v[54:55], off offset:1024
	global_load_dwordx4 v[108:111], v[54:55], off offset:2048
	global_load_dwordx4 v[112:115], v[54:55], off offset:3072
	global_load_dwordx4 v[116:119], v[56:57], off
	global_load_dwordx4 v[120:123], v[56:57], off offset:1024
	global_load_dwordx4 v[124:127], v[56:57], off offset:2048
	global_load_dwordx4 v[128:131], v[56:57], off offset:3072
	s_branch .LBB0_836

.LBB0_836:
	s_movk_i32 s2, 0xfff
	v_cmp_lt_i32_e32 vcc, s2, v48
	v_add_u32_e32 v72, s11, v48
	s_movk_i32 s2, 0x1fff
	v_cmp_gt_i32_e64 s[18:19], s10, v72
	v_cmp_lt_i32_e64 s[14:15], s2, v72
	v_add_f32_e32 v33, v28, v29
	v_add_f32_e32 v33, v33, v30
	v_add_f32_e32 v34, v24, v25
	v_add_f32_e32 v33, v33, v31
	v_add_f32_e32 v34, v34, v26
	v_add_f32_e32 v33, 0, v33
	v_add_f32_e32 v34, v34, v27
	v_add_f32_e32 v33, v33, v34
	v_add_f32_e32 v34, v20, v21
	v_add_f32_e32 v34, v34, v22
	v_add_f32_e32 v34, v34, v23
	v_add_f32_e32 v33, v33, v34
	v_add_f32_e32 v34, v16, v17
	v_add_f32_e32 v34, v34, v18
	v_add_f32_e32 v34, v34, v19
	v_add_f32_e32 v49, v33, v34
	v_pk_mul_f32 v[34:35], v[28:29], v[28:29]
	v_pk_mul_f32 v[38:39], v[24:25], v[24:25]
	v_pk_mul_f32 v[36:37], v[30:31], v[30:31]
	v_pk_mul_f32 v[40:41], v[26:27], v[26:27]
	v_pk_mul_f32 v[42:43], v[20:21], v[20:21]
	v_add_f32_e32 v38, v38, v39
	v_add_f32_e32 v34, v34, v35
	v_pk_mul_f32 v[44:45], v[22:23], v[22:23]
	v_add_f32_e32 v38, v38, v40
	v_add_f32_e32 v34, v34, v36
	v_add_f32_e32 v35, v42, v43
	v_add_f32_e32 v38, v38, v41
	v_add_f32_e32 v34, v34, v37
	v_add_f32_e32 v35, v35, v44
	v_pk_mul_f32 v[46:47], v[16:17], v[16:17]
	v_add_f32_e32 v34, v34, v38
	v_add_f32_e32 v35, v35, v45
	v_pk_mul_f32 v[74:75], v[18:19], v[18:19]
	v_add_f32_e32 v34, v34, v35
	v_add_f32_e32 v35, v46, v47
	v_add_f32_e32 v35, v35, v74
	v_add_f32_e32 v35, v35, v75
	v_add_f32_e32 v34, v34, v35
	v_add_u32_e32 v32, 0xfffff000, v48
	v_add_f32_dpp v35, v49, v49 row_ror:8 row_mask:0xf bank_mask:0xf bound_ctrl:1
	v_add_f32_dpp v34, v34, v34 row_ror:8 row_mask:0xf bank_mask:0xf bound_ctrl:1
	v_lshrrev_b32_e32 v32, 11, v32
	v_add_f32_dpp v35, v35, v35 row_ror:4 row_mask:0xf bank_mask:0xf bound_ctrl:1
	v_add_f32_dpp v34, v34, v34 row_ror:4 row_mask:0xf bank_mask:0xf bound_ctrl:1
	v_add_u32_e32 v32, 1, v32
	v_add_f32_dpp v35, v35, v35 row_ror:2 row_mask:0xf bank_mask:0xf bound_ctrl:1
	v_add_f32_dpp v34, v34, v34 row_ror:2 row_mask:0xf bank_mask:0xf bound_ctrl:1
	v_cndmask_b32_e32 v32, 0, v32, vcc
	v_add_f32_dpp v35, v35, v35 row_ror:1 row_mask:0xf bank_mask:0xf bound_ctrl:1
	v_mov_b32_e32 v36, v35
	v_add_f32_dpp v34, v34, v34 row_ror:1 row_mask:0xf bank_mask:0xf bound_ctrl:1
	s_nop 0
	v_permlane16_swap_b32_e32 v35, v36
	v_add_f32_e32 v35, v35, v36
	v_mov_b32_e32 v36, v34
	s_nop 1
	v_permlane16_swap_b32_e32 v34, v36
	v_add_f32_e32 v34, v34, v36
	s_movk_i32 s2, 0x6000
	v_mov_b32_e32 v37, v35
	v_mov_b32_e32 v36, v34
	v_mad_u64_u32 v[32:33], s[2:3], v32, s2, v[64:65]
	v_permlane32_swap_b32_e32 v35, v37
	v_permlane32_swap_b32_e32 v34, v36
	v_pk_add_f32 v[34:35], v[34:35], v[36:37]
	s_mov_b32 s2, 0x3a800000
	v_pk_mul_f32 v[74:75], v[34:35], s[2:3] op_sel_hi:[1,0]
	s_mov_b32 s2, 0x800000
	v_fma_f32 v34, -v75, v75, v74
	v_max_f32_e32 v34, 0, v34
	v_add_f32_e32 v34, 0x3727c5ac, v34
	v_cmp_gt_f32_e32 vcc, s2, v34
	v_mul_f32_e32 v35, 0x4b800000, v34
	s_mov_b64 s[2:3], 0x3000
	v_cndmask_b32_e32 v34, v34, v35, vcc
	v_rsq_f32_e32 v34, v34
	v_lshl_add_u64 v[80:81], v[32:33], 0, s[2:3]
	s_mov_b64 s[2:3], 0x4000
	v_lshl_add_u64 v[78:79], v[32:33], 0, s[2:3]
	v_mul_f32_e32 v35, 0x45800000, v34
	v_lshl_add_u64 v[40:41], v[80:81], 0, v[50:51]
	v_lshl_add_u64 v[44:45], v[78:79], 0, v[50:51]
	v_cndmask_b32_e32 v76, v34, v35, vcc
	v_lshl_add_u64 v[92:93], v[80:81], 0, v[66:67]
	v_lshl_add_u64 v[94:95], v[78:79], 0, v[66:67]
	v_lshl_add_u64 v[96:97], v[80:81], 0, v[68:69]
	v_lshl_add_u64 v[98:99], v[78:79], 0, v[68:69]
	v_lshl_add_u64 v[164:165], v[80:81], 0, v[70:71]
	v_lshl_add_u64 v[166:167], v[78:79], 0, v[70:71]
	global_load_dwordx4 v[132:135], v[40:41], off
	global_load_dwordx4 v[148:151], v[44:45], off
	global_load_dwordx4 v[136:139], v[92:93], off
	global_load_dwordx4 v[152:155], v[94:95], off
	global_load_dwordx4 v[140:143], v[96:97], off
	global_load_dwordx4 v[156:159], v[98:99], off
	global_load_dwordx4 v[144:147], v[164:165], off
	global_load_dwordx4 v[160:163], v[166:167], off
	s_and_b64 vcc, exec, s[18:19]
	s_cbranch_vccz .Lr6_dummy
	v_ashrrev_i32_e32 v73, 31, v72
	v_lshlrev_b64 v[0:1], 12, v[72:73]
	v_lshl_add_u64 v[12:13], v[58:59], 0, v[0:1]
	global_load_dwordx4 v[0:3], v[12:13], off
	global_load_dwordx4 v[4:7], v[12:13], off offset:1024
	global_load_dwordx4 v[8:11], v[12:13], off offset:2048
	s_nop 0
	global_load_dwordx4 v[12:15], v[12:13], off offset:3072
	s_branch .Lr6_join

.Lr6_join:
	v_pk_add_f32 v[28:29], v[28:29], v[74:75] op_sel:[0,1] neg_lo:[0,1] neg_hi:[0,1]
	v_pk_add_f32 v[30:31], v[30:31], v[74:75] op_sel:[0,1] neg_lo:[0,1] neg_hi:[0,1]
	v_pk_mul_f32 v[28:29], v[28:29], v[76:77] op_sel_hi:[1,0]
	v_pk_mul_f32 v[30:31], v[30:31], v[76:77] op_sel_hi:[1,0]
	v_ashrrev_i32_e32 v49, 31, v48
	v_lshlrev_b64 v[82:83], 11, v[48:49]
	v_pk_add_f32 v[24:25], v[24:25], v[74:75] op_sel:[0,1] neg_lo:[0,1] neg_hi:[0,1]
	v_pk_add_f32 v[26:27], v[26:27], v[74:75] op_sel:[0,1] neg_lo:[0,1] neg_hi:[0,1]
	v_pk_mul_f32 v[24:25], v[24:25], v[76:77] op_sel_hi:[1,0]
	v_pk_mul_f32 v[26:27], v[26:27], v[76:77] op_sel_hi:[1,0]
	v_pk_add_f32 v[20:21], v[20:21], v[74:75] op_sel:[0,1] neg_lo:[0,1] neg_hi:[0,1]
	v_pk_add_f32 v[22:23], v[22:23], v[74:75] op_sel:[0,1] neg_lo:[0,1] neg_hi:[0,1]
	v_pk_mul_f32 v[20:21], v[20:21], v[76:77] op_sel_hi:[1,0]
	v_pk_mul_f32 v[22:23], v[22:23], v[76:77] op_sel_hi:[1,0]
	v_pk_add_f32 v[16:17], v[16:17], v[74:75] op_sel:[0,1] neg_lo:[0,1] neg_hi:[0,1]
	v_pk_add_f32 v[18:19], v[18:19], v[74:75] op_sel:[0,1] neg_lo:[0,1] neg_hi:[0,1]
	v_pk_mul_f32 v[16:17], v[16:17], v[76:77] op_sel_hi:[1,0]
	v_pk_mul_f32 v[18:19], v[18:19], v[76:77] op_sel_hi:[1,0]
	s_waitcnt vmcnt(4)
	v_pk_fma_f32 v[28:29], v[100:101], v[28:29], v[116:117]
	v_pk_add_f32 v[34:35], v[148:149], 1.0 op_sel_hi:[1,0]
	v_pk_fma_f32 v[30:31], v[102:103], v[30:31], v[118:119]
	v_pk_fma_f32 v[28:29], v[34:35], v[28:29], v[132:133]
	v_pk_add_f32 v[34:35], v[150:151], 1.0 op_sel_hi:[1,0]
	s_nop 0
	v_pk_fma_f32 v[30:31], v[30:31], v[34:35], v[134:135]
	v_lshl_add_u64 v[32:33], v[62:63], 0, v[82:83]
	v_cvt_pk_bf16_f32 v36, v28, v29
	v_cvt_pk_bf16_f32 v37, v30, v31
	global_store_dwordx2 v[32:33], v[36:37], off
	v_pk_fma_f32 v[24:25], v[104:105], v[24:25], v[120:121]
	v_pk_add_f32 v[34:35], v[152:153], 1.0 op_sel_hi:[1,0]
	v_pk_fma_f32 v[26:27], v[106:107], v[26:27], v[122:123]
	v_pk_fma_f32 v[24:25], v[34:35], v[24:25], v[136:137]
	v_pk_add_f32 v[34:35], v[154:155], 1.0 op_sel_hi:[1,0]
	s_nop 0
	v_pk_fma_f32 v[26:27], v[26:27], v[34:35], v[138:139]
	v_cvt_pk_bf16_f32 v36, v24, v25
	v_cvt_pk_bf16_f32 v37, v26, v27
	global_store_dwordx2 v[32:33], v[36:37], off offset:512
	v_pk_fma_f32 v[20:21], v[108:109], v[20:21], v[124:125]
	v_pk_add_f32 v[34:35], v[156:157], 1.0 op_sel_hi:[1,0]
	v_pk_fma_f32 v[22:23], v[110:111], v[22:23], v[126:127]
	v_pk_fma_f32 v[20:21], v[34:35], v[20:21], v[140:141]
	v_pk_add_f32 v[34:35], v[158:159], 1.0 op_sel_hi:[1,0]
	s_nop 0
	v_pk_fma_f32 v[22:23], v[22:23], v[34:35], v[142:143]
	v_cvt_pk_bf16_f32 v36, v20, v21
	v_cvt_pk_bf16_f32 v37, v22, v23
	global_store_dwordx2 v[32:33], v[36:37], off offset:1024
	v_pk_fma_f32 v[16:17], v[112:113], v[16:17], v[128:129]
	v_pk_add_f32 v[34:35], v[160:161], 1.0 op_sel_hi:[1,0]
	v_pk_fma_f32 v[18:19], v[114:115], v[18:19], v[130:131]
	v_pk_fma_f32 v[16:17], v[34:35], v[16:17], v[144:145]
	v_pk_add_f32 v[34:35], v[162:163], 1.0 op_sel_hi:[1,0]
	s_nop 0
	v_pk_fma_f32 v[18:19], v[18:19], v[34:35], v[146:147]
	v_cvt_pk_bf16_f32 v36, v16, v17
	v_cvt_pk_bf16_f32 v37, v18, v19
	global_store_dwordx2 v[32:33], v[36:37], off offset:1536
	ds_read_b128 v[168:171], v52
	ds_read_b128 v[172:175], v52 offset:1024
	ds_read_b128 v[176:179], v52 offset:2048
	ds_read_b128 v[180:183], v52 offset:3072
	ds_read_b128 v[184:187], v52 offset:4096
	ds_read_b128 v[188:191], v52 offset:5120
	ds_read_b128 v[192:195], v52 offset:6144
	ds_read_b128 v[196:199], v52 offset:7168
	ds_read_b128 v[200:203], v52 offset:8192
	ds_read_b128 v[204:207], v52 offset:9216
	ds_read_b128 v[208:211], v52 offset:10240
	ds_read_b128 v[212:215], v52 offset:11264
	s_waitcnt lgkmcnt(8)
	v_pk_mul_f32 v[216:217], v[28:29], v[168:169]
	v_pk_fma_f32 v[216:217], v[30:31], v[170:171], v[216:217]
	v_pk_fma_f32 v[216:217], v[24:25], v[172:173], v[216:217]
	v_pk_fma_f32 v[216:217], v[26:27], v[174:175], v[216:217]
	v_pk_fma_f32 v[216:217], v[20:21], v[176:177], v[216:217]
	v_pk_fma_f32 v[216:217], v[22:23], v[178:179], v[216:217]
	v_pk_fma_f32 v[216:217], v[16:17], v[180:181], v[216:217]
	v_pk_fma_f32 v[216:217], v[18:19], v[182:183], v[216:217]
	ds_read_b128 v[168:171], v52 offset:12288
	ds_read_b128 v[172:175], v52 offset:13312
	ds_read_b128 v[176:179], v52 offset:14336
	ds_read_b128 v[180:183], v52 offset:15360
	v_add_f32_e32 v32, v216, v217
	s_waitcnt lgkmcnt(8)
	v_pk_mul_f32 v[216:217], v[28:29], v[184:185]
	v_pk_fma_f32 v[216:217], v[30:31], v[186:187], v[216:217]
	v_pk_fma_f32 v[216:217], v[24:25], v[188:189], v[216:217]
	v_pk_fma_f32 v[216:217], v[26:27], v[190:191], v[216:217]
	v_pk_fma_f32 v[216:217], v[20:21], v[192:193], v[216:217]
	v_pk_fma_f32 v[216:217], v[22:23], v[194:195], v[216:217]
	v_pk_fma_f32 v[216:217], v[16:17], v[196:197], v[216:217]
	v_pk_fma_f32 v[216:217], v[18:19], v[198:199], v[216:217]
	ds_read_b128 v[184:187], v52 offset:16384
	ds_read_b128 v[188:191], v52 offset:17408
	ds_read_b128 v[192:195], v52 offset:18432
	ds_read_b128 v[196:199], v52 offset:19456
	v_add_f32_e32 v33, v216, v217
	s_waitcnt lgkmcnt(8)
	v_pk_mul_f32 v[216:217], v[28:29], v[200:201]
	v_pk_fma_f32 v[216:217], v[30:31], v[202:203], v[216:217]
	v_pk_fma_f32 v[216:217], v[24:25], v[204:205], v[216:217]
	v_pk_fma_f32 v[216:217], v[26:27], v[206:207], v[216:217]
	v_pk_fma_f32 v[216:217], v[20:21], v[208:209], v[216:217]
	v_pk_fma_f32 v[216:217], v[22:23], v[210:211], v[216:217]
	v_pk_fma_f32 v[216:217], v[16:17], v[212:213], v[216:217]
	v_pk_fma_f32 v[216:217], v[18:19], v[214:215], v[216:217]
	ds_read_b128 v[200:203], v52 offset:20480
	ds_read_b128 v[204:207], v52 offset:21504
	ds_read_b128 v[208:211], v52 offset:22528
	ds_read_b128 v[212:215], v52 offset:23552
	v_add_f32_e32 v34, v216, v217
	s_waitcnt lgkmcnt(8)
	v_pk_mul_f32 v[216:217], v[28:29], v[168:169]
	v_pk_fma_f32 v[216:217], v[30:31], v[170:171], v[216:217]
	v_pk_fma_f32 v[216:217], v[24:25], v[172:173], v[216:217]
	v_pk_fma_f32 v[216:217], v[26:27], v[174:175], v[216:217]
	v_pk_fma_f32 v[216:217], v[20:21], v[176:177], v[216:217]
	v_pk_fma_f32 v[216:217], v[22:23], v[178:179], v[216:217]
	v_pk_fma_f32 v[216:217], v[16:17], v[180:181], v[216:217]
	v_pk_fma_f32 v[216:217], v[18:19], v[182:183], v[216:217]
	ds_read_b128 v[168:171], v52 offset:24576
	ds_read_b128 v[172:175], v52 offset:25600
	ds_read_b128 v[176:179], v52 offset:26624
	ds_read_b128 v[180:183], v52 offset:27648
	v_add_f32_e32 v35, v216, v217
	s_waitcnt lgkmcnt(8)
	v_pk_mul_f32 v[216:217], v[28:29], v[184:185]
	v_pk_fma_f32 v[216:217], v[30:31], v[186:187], v[216:217]
	v_pk_fma_f32 v[216:217], v[24:25], v[188:189], v[216:217]
	v_pk_fma_f32 v[216:217], v[26:27], v[190:191], v[216:217]
	v_pk_fma_f32 v[216:217], v[20:21], v[192:193], v[216:217]
	v_pk_fma_f32 v[216:217], v[22:23], v[194:195], v[216:217]
	v_pk_fma_f32 v[216:217], v[16:17], v[196:197], v[216:217]
	v_pk_fma_f32 v[216:217], v[18:19], v[198:199], v[216:217]
	ds_read_b128 v[184:187], v52 offset:28672
	ds_read_b128 v[188:191], v52 offset:29696
	ds_read_b128 v[192:195], v52 offset:30720
	ds_read_b128 v[196:199], v52 offset:31744
	v_add_f32_e32 v36, v216, v217
	s_waitcnt lgkmcnt(8)
	v_pk_mul_f32 v[216:217], v[28:29], v[200:201]
	v_pk_fma_f32 v[216:217], v[30:31], v[202:203], v[216:217]
	v_pk_fma_f32 v[216:217], v[24:25], v[204:205], v[216:217]
	v_pk_fma_f32 v[216:217], v[26:27], v[206:207], v[216:217]
	v_pk_fma_f32 v[216:217], v[20:21], v[208:209], v[216:217]
	v_pk_fma_f32 v[216:217], v[22:23], v[210:211], v[216:217]
	v_pk_fma_f32 v[216:217], v[16:17], v[212:213], v[216:217]
	v_pk_fma_f32 v[216:217], v[18:19], v[214:215], v[216:217]
	ds_read_b128 v[200:203], v52 offset:32768
	ds_read_b128 v[204:207], v52 offset:33792
	ds_read_b128 v[208:211], v52 offset:34816
	ds_read_b128 v[212:215], v52 offset:35840
	v_add_f32_e32 v37, v216, v217
	s_waitcnt lgkmcnt(8)
	v_pk_mul_f32 v[216:217], v[28:29], v[168:169]
	v_pk_fma_f32 v[216:217], v[30:31], v[170:171], v[216:217]
	v_pk_fma_f32 v[216:217], v[24:25], v[172:173], v[216:217]
	v_pk_fma_f32 v[216:217], v[26:27], v[174:175], v[216:217]
	v_pk_fma_f32 v[216:217], v[20:21], v[176:177], v[216:217]
	v_pk_fma_f32 v[216:217], v[22:23], v[178:179], v[216:217]
	v_pk_fma_f32 v[216:217], v[16:17], v[180:181], v[216:217]
	v_pk_fma_f32 v[216:217], v[18:19], v[182:183], v[216:217]
	ds_read_b128 v[168:171], v52 offset:36864
	ds_read_b128 v[172:175], v52 offset:37888
	ds_read_b128 v[176:179], v52 offset:38912
	ds_read_b128 v[180:183], v52 offset:39936
	v_add_f32_e32 v46, v216, v217
	s_waitcnt lgkmcnt(8)
	v_pk_mul_f32 v[216:217], v[28:29], v[184:185]
	v_pk_fma_f32 v[216:217], v[30:31], v[186:187], v[216:217]
	v_pk_fma_f32 v[216:217], v[24:25], v[188:189], v[216:217]
	v_pk_fma_f32 v[216:217], v[26:27], v[190:191], v[216:217]
	v_pk_fma_f32 v[216:217], v[20:21], v[192:193], v[216:217]
	v_pk_fma_f32 v[216:217], v[22:23], v[194:195], v[216:217]
	v_pk_fma_f32 v[216:217], v[16:17], v[196:197], v[216:217]
	v_pk_fma_f32 v[216:217], v[18:19], v[198:199], v[216:217]
	ds_read_b128 v[184:187], v52 offset:40960
	ds_read_b128 v[188:191], v52 offset:41984
	ds_read_b128 v[192:195], v52 offset:43008
	ds_read_b128 v[196:199], v52 offset:44032
	v_add_f32_e32 v47, v216, v217
	s_waitcnt lgkmcnt(8)
	v_pk_mul_f32 v[216:217], v[28:29], v[200:201]
	v_pk_fma_f32 v[216:217], v[30:31], v[202:203], v[216:217]
	v_pk_fma_f32 v[216:217], v[24:25], v[204:205], v[216:217]
	v_pk_fma_f32 v[216:217], v[26:27], v[206:207], v[216:217]
	v_pk_fma_f32 v[216:217], v[20:21], v[208:209], v[216:217]
	v_pk_fma_f32 v[216:217], v[22:23], v[210:211], v[216:217]
	v_pk_fma_f32 v[216:217], v[16:17], v[212:213], v[216:217]
	v_pk_fma_f32 v[216:217], v[18:19], v[214:215], v[216:217]
	ds_read_b128 v[200:203], v52 offset:45056
	ds_read_b128 v[204:207], v52 offset:46080
	ds_read_b128 v[208:211], v52 offset:47104
	ds_read_b128 v[212:215], v52 offset:48128
	v_add_f32_e32 v73, v216, v217
	s_waitcnt lgkmcnt(8)
	v_pk_mul_f32 v[216:217], v[28:29], v[168:169]
	v_pk_fma_f32 v[216:217], v[30:31], v[170:171], v[216:217]
	v_pk_fma_f32 v[216:217], v[24:25], v[172:173], v[216:217]
	v_pk_fma_f32 v[216:217], v[26:27], v[174:175], v[216:217]
	v_pk_fma_f32 v[216:217], v[20:21], v[176:177], v[216:217]
	v_pk_fma_f32 v[216:217], v[22:23], v[178:179], v[216:217]
	v_pk_fma_f32 v[216:217], v[16:17], v[180:181], v[216:217]
	v_pk_fma_f32 v[216:217], v[18:19], v[182:183], v[216:217]
	ds_read_b128 v[168:171], v52 offset:49152
	ds_read_b128 v[172:175], v52 offset:50176
	ds_read_b128 v[176:179], v52 offset:51200
	ds_read_b128 v[180:183], v52 offset:52224
	v_add_f32_e32 v74, v216, v217
	s_waitcnt lgkmcnt(8)
	v_pk_mul_f32 v[216:217], v[28:29], v[184:185]
	v_pk_fma_f32 v[216:217], v[30:31], v[186:187], v[216:217]
	v_pk_fma_f32 v[216:217], v[24:25], v[188:189], v[216:217]
	v_pk_fma_f32 v[216:217], v[26:27], v[190:191], v[216:217]
	v_pk_fma_f32 v[216:217], v[20:21], v[192:193], v[216:217]
	v_pk_fma_f32 v[216:217], v[22:23], v[194:195], v[216:217]
	v_pk_fma_f32 v[216:217], v[16:17], v[196:197], v[216:217]
	v_pk_fma_f32 v[216:217], v[18:19], v[198:199], v[216:217]
	ds_read_b128 v[184:187], v52 offset:53248
	ds_read_b128 v[188:191], v52 offset:54272
	ds_read_b128 v[192:195], v52 offset:55296
	ds_read_b128 v[196:199], v52 offset:56320
	v_add_f32_e32 v75, v216, v217
	s_waitcnt lgkmcnt(8)
	v_pk_mul_f32 v[216:217], v[28:29], v[200:201]
	v_pk_fma_f32 v[216:217], v[30:31], v[202:203], v[216:217]
	v_pk_fma_f32 v[216:217], v[24:25], v[204:205], v[216:217]
	v_pk_fma_f32 v[216:217], v[26:27], v[206:207], v[216:217]
	v_pk_fma_f32 v[216:217], v[20:21], v[208:209], v[216:217]
	v_pk_fma_f32 v[216:217], v[22:23], v[210:211], v[216:217]
	v_pk_fma_f32 v[216:217], v[16:17], v[212:213], v[216:217]
	v_pk_fma_f32 v[216:217], v[18:19], v[214:215], v[216:217]
	ds_read_b128 v[200:203], v52 offset:57344
	ds_read_b128 v[204:207], v52 offset:58368
	ds_read_b128 v[208:211], v52 offset:59392
	ds_read_b128 v[212:215], v52 offset:60416
	v_add_f32_e32 v76, v216, v217
	s_waitcnt lgkmcnt(8)
	v_pk_mul_f32 v[216:217], v[28:29], v[168:169]
	v_pk_fma_f32 v[216:217], v[30:31], v[170:171], v[216:217]
	v_pk_fma_f32 v[216:217], v[24:25], v[172:173], v[216:217]
	v_pk_fma_f32 v[216:217], v[26:27], v[174:175], v[216:217]
	v_pk_fma_f32 v[216:217], v[20:21], v[176:177], v[216:217]
	v_pk_fma_f32 v[216:217], v[22:23], v[178:179], v[216:217]
	v_pk_fma_f32 v[216:217], v[16:17], v[180:181], v[216:217]
	v_pk_fma_f32 v[216:217], v[18:19], v[182:183], v[216:217]
	ds_read_b128 v[168:171], v52 offset:61440
	ds_read_b128 v[172:175], v52 offset:62464
	ds_read_b128 v[176:179], v52 offset:63488
	ds_read_b128 v[180:183], v52 offset:64512
	v_add_f32_e32 v82, v216, v217
	s_waitcnt lgkmcnt(8)
	v_pk_mul_f32 v[216:217], v[28:29], v[184:185]
	v_pk_fma_f32 v[216:217], v[30:31], v[186:187], v[216:217]
	v_pk_fma_f32 v[216:217], v[24:25], v[188:189], v[216:217]
	v_pk_fma_f32 v[216:217], v[26:27], v[190:191], v[216:217]
	v_pk_fma_f32 v[216:217], v[20:21], v[192:193], v[216:217]
	v_pk_fma_f32 v[216:217], v[22:23], v[194:195], v[216:217]
	v_pk_fma_f32 v[216:217], v[16:17], v[196:197], v[216:217]
	v_pk_fma_f32 v[216:217], v[18:19], v[198:199], v[216:217]
	v_add_f32_e32 v83, v216, v217
	s_waitcnt lgkmcnt(4)
	v_pk_mul_f32 v[216:217], v[28:29], v[200:201]
	v_pk_fma_f32 v[216:217], v[30:31], v[202:203], v[216:217]
	v_pk_fma_f32 v[216:217], v[24:25], v[204:205], v[216:217]
	v_pk_fma_f32 v[216:217], v[26:27], v[206:207], v[216:217]
	v_pk_fma_f32 v[216:217], v[20:21], v[208:209], v[216:217]
	v_pk_fma_f32 v[216:217], v[22:23], v[210:211], v[216:217]
	v_pk_fma_f32 v[216:217], v[16:17], v[212:213], v[216:217]
	v_pk_fma_f32 v[216:217], v[18:19], v[214:215], v[216:217]
	v_add_f32_e32 v87, v216, v217
	s_waitcnt lgkmcnt(0)
	v_pk_mul_f32 v[216:217], v[28:29], v[168:169]
	v_pk_fma_f32 v[216:217], v[30:31], v[170:171], v[216:217]
	v_pk_fma_f32 v[216:217], v[24:25], v[172:173], v[216:217]
	v_pk_fma_f32 v[216:217], v[26:27], v[174:175], v[216:217]
	v_pk_fma_f32 v[216:217], v[20:21], v[176:177], v[216:217]
	v_pk_fma_f32 v[216:217], v[22:23], v[178:179], v[216:217]
	v_pk_fma_f32 v[216:217], v[16:17], v[180:181], v[216:217]
	v_pk_fma_f32 v[216:217], v[18:19], v[182:183], v[216:217]
	v_add_f32_e32 v16, v216, v217
	v_cndmask_b32_e64 v18, v32, v73, s[34:35]
	v_mov_b32_e32 v19, v18
	s_nop 1
	v_permlane32_swap_b32_e32 v18, v19
	v_cndmask_b32_e64 v18, v18, v19, s[34:35]
	v_cndmask_b32_e64 v19, v33, v74, s[34:35]
	v_mov_b32_e32 v20, v19
	s_nop 1
	v_permlane32_swap_b32_e32 v19, v20
	v_cndmask_b32_e64 v19, v19, v20, s[34:35]
	v_cndmask_b32_e64 v20, v34, v75, s[34:35]
	v_mov_b32_e32 v21, v20
	s_nop 1
	v_permlane32_swap_b32_e32 v20, v21
	v_cndmask_b32_e64 v20, v20, v21, s[34:35]
	v_cndmask_b32_e64 v21, v35, v76, s[34:35]
	v_mov_b32_e32 v22, v21
	s_nop 1
	v_permlane32_swap_b32_e32 v21, v22
	v_cndmask_b32_e64 v21, v21, v22, s[34:35]
	v_cndmask_b32_e64 v22, v36, v82, s[34:35]
	v_mov_b32_e32 v23, v22
	s_nop 1
	v_permlane32_swap_b32_e32 v22, v23
	v_cndmask_b32_e64 v17, v73, v32, s[34:35]
	v_cndmask_b32_e64 v22, v22, v23, s[34:35]
	v_cndmask_b32_e64 v23, v37, v83, s[34:35]
	v_add_f32_e32 v17, v17, v18
	v_cndmask_b32_e64 v18, v74, v33, s[34:35]
	v_mov_b32_e32 v24, v23
	v_add_f32_e32 v18, v18, v19
	v_cndmask_b32_e64 v19, v75, v34, s[34:35]
	v_permlane32_swap_b32_e32 v23, v24
	v_add_f32_e32 v19, v19, v20
	v_cndmask_b32_e64 v20, v76, v35, s[34:35]
	v_cndmask_b32_e64 v23, v23, v24, s[34:35]
	v_cndmask_b32_e64 v24, v46, v87, s[34:35]
	v_add_f32_e32 v20, v20, v21
	v_cndmask_b32_e64 v21, v82, v36, s[34:35]
	v_mov_b32_e32 v25, v24
	v_add_f32_e32 v21, v21, v22
	v_cndmask_b32_e64 v22, v83, v37, s[34:35]
	v_permlane32_swap_b32_e32 v24, v25
	v_add_f32_e32 v22, v22, v23
	v_cndmask_b32_e64 v23, v87, v46, s[34:35]
	v_cndmask_b32_e64 v24, v24, v25, s[34:35]
	v_add_f32_e32 v23, v23, v24
	v_cndmask_b32_e64 v24, v16, v47, s[34:35]
	v_cndmask_b32_e64 v16, v47, v16, s[34:35]
	v_mov_b32_e32 v25, v16
	s_nop 1
	v_permlane32_swap_b32_e32 v16, v25
	v_cndmask_b32_e64 v16, v16, v25, s[34:35]
	v_add_f32_e32 v16, v24, v16
	v_cndmask_b32_e64 v24, v21, v17, s[4:5]
	v_cndmask_b32_e64 v17, v17, v21, s[4:5]
	v_mov_b32_e32 v21, v17
	s_nop 1
	v_permlane16_swap_b32_e32 v17, v21
	v_cndmask_b32_e64 v17, v17, v21, s[4:5]
	v_cndmask_b32_e64 v21, v22, v18, s[4:5]
	v_cndmask_b32_e64 v18, v18, v22, s[4:5]
	v_mov_b32_e32 v22, v18
	s_nop 1
	v_permlane16_swap_b32_e32 v18, v22
	v_cndmask_b32_e64 v18, v18, v22, s[4:5]
	v_add_f32_e32 v18, v21, v18
	v_cndmask_b32_e64 v21, v23, v19, s[4:5]
	v_cndmask_b32_e64 v19, v19, v23, s[4:5]
	v_mov_b32_e32 v22, v19
	s_nop 1
	v_permlane16_swap_b32_e32 v19, v22
	v_cndmask_b32_e64 v19, v19, v22, s[4:5]
	v_add_f32_e32 v19, v21, v19
	v_cndmask_b32_e64 v21, v16, v20, s[4:5]
	v_cndmask_b32_e64 v16, v20, v16, s[4:5]
	v_mov_b32_e32 v20, v16
	s_nop 1
	v_permlane16_swap_b32_e32 v16, v20
	v_cndmask_b32_e64 v16, v16, v20, s[4:5]
	v_add_f32_e32 v17, v24, v17
	v_add_f32_e32 v16, v21, v16
	v_cndmask_b32_e64 v20, v17, v19, s[6:7]
	v_cndmask_b32_e64 v21, v18, v16, s[6:7]
	ds_bpermute_b32 v20, v77, v20
	ds_bpermute_b32 v21, v77, v21
	v_cndmask_b32_e64 v17, v19, v17, s[6:7]
	v_cndmask_b32_e64 v16, v16, v18, s[6:7]
	s_mov_b32 s2, 0x3fb8aa3b
	s_waitcnt lgkmcnt(1)
	v_add_f32_e32 v17, v17, v20
	s_waitcnt lgkmcnt(0)
	v_add_f32_e32 v16, v16, v21
	v_cndmask_b32_e64 v18, v17, v16, s[8:9]
	ds_bpermute_b32 v18, v84, v18
	v_cndmask_b32_e64 v16, v16, v17, s[8:9]
	s_waitcnt lgkmcnt(0)
	v_add_f32_e32 v16, v16, v18
	ds_bpermute_b32 v17, v85, v16
	s_waitcnt lgkmcnt(0)
	v_add_f32_e32 v16, v16, v17
	ds_bpermute_b32 v17, v86, v16
	s_waitcnt lgkmcnt(0)
	v_add_f32_e32 v16, v16, v17
	ds_bpermute_b32 v17, v77, v16
	s_waitcnt lgkmcnt(0)
	v_max_f32_e32 v17, v17, v17
	v_max_f32_e32 v17, v16, v17
	ds_bpermute_b32 v18, v84, v17
	s_waitcnt lgkmcnt(0)
	v_max_f32_e32 v18, v18, v18
	v_max_f32_e32 v17, v17, v18
	v_mov_b32_e32 v18, v17
	s_nop 1
	v_permlane16_swap_b32_e32 v17, v18
	v_max_f32_e32 v18, v18, v18
	v_max_f32_e32 v17, v17, v17
	v_max_f32_e32 v17, v17, v18
	v_mov_b32_e32 v18, v17
	s_nop 1
	v_permlane32_swap_b32_e32 v17, v18
	v_max_f32_e32 v18, v18, v18
	v_max_f32_e32 v17, v17, v17
	v_max_f32_e32 v17, v17, v18
	v_sub_f32_e32 v16, v16, v17
	v_mul_f32_e32 v17, 0x3fb8aa3b, v16
	v_fma_f32 v18, v16, s2, -v17
	v_rndne_f32_e32 v19, v17
	v_fmac_f32_e32 v18, 0x32a5705f, v16
	v_sub_f32_e32 v17, v17, v19
	v_add_f32_e32 v17, v17, v18
	v_exp_f32_e32 v17, v17
	v_cvt_i32_f32_e32 v18, v19
	s_mov_b32 s2, 0xc2ce8ed0
	v_cmp_ngt_f32_e32 vcc, s2, v16
	s_mov_b32 s2, 0x42b17218
	v_ldexp_f32 v17, v17, v18
	v_cndmask_b32_e32 v17, 0, v17, vcc
	v_cmp_nlt_f32_e32 vcc, s2, v16
	s_nop 1
	v_cndmask_b32_e32 v16, v53, v17, vcc
	ds_bpermute_b32 v17, v77, v16
	s_waitcnt lgkmcnt(0)
	v_add_f32_e32 v17, v16, v17
	ds_bpermute_b32 v18, v84, v17
	s_waitcnt lgkmcnt(0)
	v_add_f32_e32 v17, v17, v18
	v_mov_b32_e32 v18, v17
	s_nop 1
	v_permlane16_swap_b32_e32 v17, v18
	v_add_f32_e32 v17, v17, v18
	v_mov_b32_e32 v18, v17
	s_nop 1
	v_permlane32_swap_b32_e32 v17, v18
	s_and_saveexec_b64 s[2:3], s[0:1]
	s_cbranch_execz .LBB0_840
	v_add_f32_e32 v17, v17, v18
	v_div_scale_f32 v18, s[18:19], v17, v17, v16
	v_rcp_f32_e32 v19, v18
	v_div_scale_f32 v20, vcc, v16, v17, v16
	v_fma_f32 v21, -v18, v19, 1.0
	v_fmac_f32_e32 v19, v21, v19
	v_mul_f32_e32 v21, v20, v19
	v_fma_f32 v22, -v18, v21, v20
	v_fmac_f32_e32 v21, v22, v19
	v_fma_f32 v18, -v18, v21, v20
	v_div_fmas_f32 v18, v18, v19, v21
	v_div_fixup_f32 v18, v18, v17, v16
	v_lshlrev_b64 v[16:17], 6, v[48:49]
	v_lshl_add_u64 v[16:17], v[60:61], 0, v[16:17]
	global_store_dword v[16:17], v18, off
